# GEMM1 per-XCD rotation offsets changed to xcd+2 so the partial 12th round holds light u tiles
# speedup vs baseline: 1.0044x; 1.0001x over previous
;     __host__ __device__ bool next(int i, Unit& u) const {
;         const long L = (long)i * G + c; if (L >= nwg) return false;
;         int wgid = (int)L; { const int q = nwg / NXCD, r = nwg % NXCD, xcd = wgid % NXCD, off = wgid / NXCD; wgid = (xcd < r ? xcd * (q + 1) : r * (q + 1) + (xcd - r) * q) + off; }
;         const int nig = WGM * nN, gid = wgid / nig, fm = gid * WGM, gsz = (nM - fm) < WGM ? (nM - fm) : WGM;
;         u.pm = fm + ((wgid % nig) % gsz); u.pn = (wgid % nig) / gsz; return true;
;     }
; __global__ void __launch_bounds__(512, 2) fwd_kernel(Args a) {
;     ...
;         { pg8::Gemm g{(const bf16_t*)(P.ws + WS_H), (const bf16_t*)(P.ws + WS_WIN), T, 5888, DM}; pg8::StaticOrder S; S.init(T, 5888, G, bx);
;           EpiInProj E{P.ws, P.out};
;           pg8::gemm_phase<EpiInProj, pg8::StaticOrder, true, true>(lds, g, S, E); }
.LBB0_339:
	s_cmp_lt_i32 s92, 3
	s_cselect_b64 s[2:3], -1, 0
	s_and_b64 s[0:1], s[2:3], s[0:1]
	s_andn2_b64 vcc, exec, s[0:1]
	s_mov_b64 s[0:1], s[48:49]
	s_mov_b64 s[14:15], s[62:63]
	v_writelane_b32 v254, s0, 23
	s_nop 1
	v_writelane_b32 v254, s1, 24
	v_writelane_b32 v254, s2, 25
	v_writelane_b32 v254, s3, 26
	v_writelane_b32 v254, s4, 27
	v_writelane_b32 v254, s5, 28
	v_writelane_b32 v254, s6, 29
	v_writelane_b32 v254, s7, 30
	v_writelane_b32 v254, s8, 31
	v_writelane_b32 v254, s9, 32
	v_writelane_b32 v254, s10, 33
	v_writelane_b32 v254, s11, 34
	v_writelane_b32 v254, s12, 35
	v_writelane_b32 v254, s13, 36
	v_writelane_b32 v254, s14, 37
	v_writelane_b32 v254, s15, 38
	s_cbranch_vccnz .LBB0_1057
	s_cmpk_lt_i32 s80, 0xb80
	v_readfirstlane_b32 s11, v200
	s_movk_i32 s0, 0x400
	s_cselect_b64 s[2:3], -1, 0
	s_cmpk_gt_i32 s80, 0xb7f
	s_cbranch_scc1 .LBB0_342
	s_ashr_i32 s1, s80, 31
	s_lshr_b32 s1, s1, 29
	s_add_i32 s1, s80, s1
	s_ashr_i32 s4, s1, 3
	s_and_b32 s1, s1, -8
	s_sub_i32 s1, s80, s1
	s_cmp_lt_i32 s1, 0
	s_movk_i32 s5, 0x171
	s_cselect_b32 s5, s5, 0x170
	s_mul_i32 s1, s1, s5
	s_add_i32 s1, s1, s4
	s_mul_hi_i32 s4, s1, 0xb21642c9
	s_add_i32 s4, s4, s1
	s_lshr_b32 s5, s4, 31
	s_ashr_i32 s4, s4, 7
	s_add_i32 s4, s4, s5
	s_lshl_b32 s5, s4, 3
	s_mulk_i32 s4, 0xb8
	s_sub_i32 s1, s1, s4
	s_sext_i32_i16 s4, s1
	s_bfe_u32 s4, s4, 0x3001c
	s_add_i32 s4, s1, s4
	s_sext_i32_i16 s6, s4
	s_and_b32 s4, s4, 0xfff8
	s_sub_i32 s1, s1, s4
	s_sext_i32_i16 s1, s1
	s_add_i32 s33, s5, s1
	s_ashr_i32 s10, s6, 3
	s_and_b32 s32, s80, 7
	s_add_i32 s32, s32, 2
	s_add_i32 s10, s10, s32
	s_sub_i32 s1, s10, 23
	s_cmp_ge_i32 s10, 23
	s_cselect_b32 s10, s1, s10
